# strategy 7 cont.: last (xor 32) step of the 64-lane RMSNorm sums via v_permlane32_swap instead of a ds_bpermute round trip
# speedup vs baseline: 1.0092x; 1.0092x over previous
; __device__ __forceinline__ unsigned cvt_pk_bf16(float lo, float hi) { f32x2 v = {lo, hi}; bf16x2_t r = __builtin_convertvector(v, bf16x2_t); return __builtin_bit_cast(unsigned, r); }
; __device__ __forceinline__ float wave_sum(float v) {
; #pragma unroll
;     for (int o = 1; o < 64; o <<= 1) v += __shfl_xor(v, o);
;     return v;
; __device__ __forceinline__ void phase_g(KA a, int layer, const float* x1, unsigned char* lds, const int tid_, const int bid_) {
;     ...
;     for (int m = gw; m < T_; m += NGW) {
;         const f32x4* xr = (const f32x4*)(x1 + (size_t)m * D_) + lane;
;         f32x4 v[8]; float ss = 0.f;
; #pragma unroll
;         for (int j = 0; j < 8; ++j) { v[j] = xr[64 * j]; ss += (v[j].x * v[j].x + v[j].y * v[j].y) + (v[j].z * v[j].z + v[j].w * v[j].w); }
;         ss = wave_sum(ss);
;         const float rstd = rsqrtf(ss * (1.0f / D_) + 1e-6f);
;         u32x2* o8 = (u32x2*)(H + (size_t)m * D_) + lane;
; #pragma unroll
;         for (int j = 0; j < 8; ++j) { v[j] = v[j] * rstd * gn[j]; u32x2 w; w.x = cvt_pk_bf16(v[j].x, v[j].y); w.y = cvt_pk_bf16(v[j].z, v[j].w); o8[64 * j] = w; }
.LBB0_50:
	global_load_dwordx4 v[38:41], v[44:45], off offset:-4096
	global_load_dwordx4 v[34:37], v[44:45], off offset:-3072
	global_load_dwordx4 v[56:59], v[44:45], off offset:-2048
	global_load_dwordx4 v[60:63], v[44:45], off offset:-1024
	global_load_dwordx4 v[64:67], v[44:45], off
	global_load_dwordx4 v[68:71], v[44:45], off offset:1024
	global_load_dwordx4 v[72:75], v[44:45], off offset:2048
	global_load_dwordx4 v[76:79], v[44:45], off offset:3072
	v_add_u32_e32 v42, s8, v42
	s_waitcnt vmcnt(6)
	v_mov_b32_e32 v158, v39
	v_mov_b32_e32 v159, v35
	v_mov_b32_e32 v156, v38
	v_mov_b32_e32 v157, v34
	v_pk_mul_f32 v[158:159], v[158:159], v[158:159]
	v_mov_b32_e32 v160, v41
	v_mov_b32_e32 v161, v37
	v_pk_fma_f32 v[156:157], v[156:157], v[156:157], v[158:159]
	v_mov_b32_e32 v158, v40
	v_mov_b32_e32 v159, v36
	v_pk_mul_f32 v[160:161], v[160:161], v[160:161]
	s_nop 0
	v_pk_fma_f32 v[158:159], v[158:159], v[158:159], v[160:161]
	s_nop 0
	v_pk_add_f32 v[168:169], v[156:157], v[158:159]
	v_pk_add_f32 v[168:169], v[168:169], v[168:169] op_sel:[0,1] op_sel_hi:[1,0]
	s_waitcnt vmcnt(5)
	v_pk_mul_f32 v[160:161], v[58:59], v[58:59]
	v_pk_mul_f32 v[162:163], v[56:57], v[56:57]
	s_nop 0
	v_pk_mov_b32 v[164:165], v[162:163], v[160:161] op_sel:[1,0]
	v_mov_b32_e32 v163, v161
	v_pk_add_f32 v[170:171], v[164:165], v[162:163]
	v_pk_add_f32 v[170:171], v[170:171], v[170:171] op_sel:[0,1] op_sel_hi:[1,0]
	s_waitcnt vmcnt(3)
	v_mul_f32_e32 v0, v64, v64
	v_mul_f32_e32 v43, v65, v65
	v_mov_b32_e32 v169, v0
	v_mov_b32_e32 v171, v43
	v_mul_f32_e32 v0, v61, v61
	v_pk_add_f32 v[168:169], v[168:169], v[170:171]
	v_pk_fma_f32 v[170:171], v[60:61], v[60:61], v[0:1] op_sel_hi:[1,1,0]
	v_mul_f32_e32 v0, v63, v63
	v_mul_f32_e32 v48, v66, v66
	v_mul_f32_e32 v55, v67, v67
	v_pk_fma_f32 v[172:173], v[62:63], v[62:63], v[0:1] op_sel_hi:[1,1,0]
	v_mov_b32_e32 v171, v48
	v_mov_b32_e32 v173, v55
	v_pk_add_f32 v[170:171], v[170:171], v[172:173]
	s_nop 0
	v_pk_add_f32 v[80:81], v[168:169], v[170:171]
	v_pk_add_f32 v[80:81], v[80:81], v[80:81] op_sel:[0,1] op_sel_hi:[1,0]
	s_waitcnt vmcnt(2)
	v_pk_mul_f32 v[172:173], v[70:71], v[70:71]
	v_pk_mul_f32 v[174:175], v[68:69], v[68:69]
	s_nop 0
	v_pk_mov_b32 v[176:177], v[174:175], v[172:173] op_sel:[1,0]
	v_mov_b32_e32 v175, v173
	v_pk_add_f32 v[82:83], v[176:177], v[174:175]
	v_pk_add_f32 v[82:83], v[82:83], v[82:83] op_sel:[0,1] op_sel_hi:[1,0]
	v_lshl_add_u64 v[44:45], v[44:45], 0, s[12:13]
	s_waitcnt vmcnt(0)
	v_mul_f32_e32 v0, v76, v76
	v_mul_f32_e32 v43, v77, v77
	v_mov_b32_e32 v81, v0
	v_mov_b32_e32 v83, v43
	v_mul_f32_e32 v0, v73, v73
	v_pk_add_f32 v[80:81], v[80:81], v[82:83]
	v_pk_fma_f32 v[82:83], v[72:73], v[72:73], v[0:1] op_sel_hi:[1,1,0]
	v_mul_f32_e32 v0, v75, v75
	v_mul_f32_e32 v48, v78, v78
	v_mul_f32_e32 v55, v79, v79
	v_pk_fma_f32 v[84:85], v[74:75], v[74:75], v[0:1] op_sel_hi:[1,1,0]
	v_mov_b32_e32 v83, v48
	v_mov_b32_e32 v85, v55
	v_pk_add_f32 v[82:83], v[82:83], v[84:85]
	s_nop 0
	v_pk_add_f32 v[80:81], v[80:81], v[82:83]
	s_nop 0
	v_add_f32_e32 v0, v80, v81
	s_nop 1
	v_add_f32_dpp v0, v0, v0 quad_perm:[1,0,3,2] row_mask:0xf bank_mask:0xf
	s_waitcnt lgkmcnt(0)
	s_nop 1
	v_add_f32_dpp v0, v0, v0 quad_perm:[2,3,0,1] row_mask:0xf bank_mask:0xf
	s_waitcnt lgkmcnt(0)
	s_nop 1
	v_add_f32_dpp v0, v0, v0 row_half_mirror row_mask:0xf bank_mask:0xf
	s_waitcnt lgkmcnt(0)
	s_nop 1
	v_add_f32_dpp v0, v0, v0 row_mirror row_mask:0xf bank_mask:0xf
	s_waitcnt lgkmcnt(0)
	ds_bpermute_b32 v43, v53, v0
	s_waitcnt lgkmcnt(0)
	v_add_f32_e32 v0, v0, v43
	v_mov_b32_e32 v43, v0
	s_nop 1
	v_permlane32_swap_b32_e32 v0, v43
	s_waitcnt lgkmcnt(0)
	v_add_f32_e32 v0, v0, v43
	v_fmamk_f32 v0, v0, 0x3a000000, v227
	v_cmp_gt_f32_e32 vcc, s24, v0
	v_mul_f32_e32 v43, 0x4b800000, v0
	s_nop 0
	v_cndmask_b32_e32 v0, v0, v43, vcc
	v_rsq_f32_e32 v0, v0
	s_nop 0
	v_mul_f32_e32 v43, 0x45800000, v0
	v_cndmask_b32_e32 v0, v0, v43, vcc
	v_pk_mul_f32 v[34:35], v[34:35], v[0:1] op_sel_hi:[1,0]
	v_pk_mul_f32 v[36:37], v[36:37], v[0:1] op_sel_hi:[1,0]
	v_pk_mul_f32 v[34:35], v[6:7], v[34:35]
	v_pk_mul_f32 v[36:37], v[8:9], v[36:37]
	v_cvt_pk_bf16_f32 v34, v34, v35
	v_cvt_pk_bf16_f32 v35, v36, v37
	global_store_dwordx2 v[46:47], v[34:35], off offset:-3072
	v_pk_mul_f32 v[34:35], v[56:57], v[0:1] op_sel_hi:[1,0]
	v_pk_mul_f32 v[36:37], v[58:59], v[0:1] op_sel_hi:[1,0]
	v_pk_mul_f32 v[34:35], v[10:11], v[34:35]
	v_pk_mul_f32 v[36:37], v[12:13], v[36:37]
	v_cvt_pk_bf16_f32 v34, v34, v35
	v_cvt_pk_bf16_f32 v35, v36, v37
	global_store_dwordx2 v[46:47], v[34:35], off offset:-2560
	v_pk_mul_f32 v[34:35], v[60:61], v[0:1] op_sel_hi:[1,0]
	v_pk_mul_f32 v[36:37], v[62:63], v[0:1] op_sel_hi:[1,0]
	v_pk_mul_f32 v[34:35], v[14:15], v[34:35]
	v_pk_mul_f32 v[36:37], v[16:17], v[36:37]
	v_cvt_pk_bf16_f32 v34, v34, v35
	v_cvt_pk_bf16_f32 v35, v36, v37
	global_store_dwordx2 v[46:47], v[34:35], off offset:-2048
	v_pk_mul_f32 v[34:35], v[64:65], v[0:1] op_sel_hi:[1,0]
	v_pk_mul_f32 v[36:37], v[66:67], v[0:1] op_sel_hi:[1,0]
	v_pk_mul_f32 v[34:35], v[18:19], v[34:35]
	v_pk_mul_f32 v[36:37], v[20:21], v[36:37]
	v_cvt_pk_bf16_f32 v34, v34, v35
	v_cvt_pk_bf16_f32 v35, v36, v37
	global_store_dwordx2 v[46:47], v[34:35], off offset:-1536
	v_pk_mul_f32 v[34:35], v[68:69], v[0:1] op_sel_hi:[1,0]
	v_pk_mul_f32 v[36:37], v[70:71], v[0:1] op_sel_hi:[1,0]
	v_pk_mul_f32 v[34:35], v[22:23], v[34:35]
	v_pk_mul_f32 v[36:37], v[24:25], v[36:37]
	v_cvt_pk_bf16_f32 v34, v34, v35
	v_cvt_pk_bf16_f32 v35, v36, v37
	global_store_dwordx2 v[46:47], v[34:35], off offset:-1024
	v_pk_mul_f32 v[34:35], v[72:73], v[0:1] op_sel_hi:[1,0]
	v_pk_mul_f32 v[36:37], v[74:75], v[0:1] op_sel_hi:[1,0]
	v_pk_mul_f32 v[34:35], v[26:27], v[34:35]
	v_pk_mul_f32 v[36:37], v[28:29], v[36:37]
	v_cvt_pk_bf16_f32 v34, v34, v35
	v_cvt_pk_bf16_f32 v35, v36, v37
	v_pk_mul_f32 v[38:39], v[38:39], v[0:1] op_sel_hi:[1,0]
	v_pk_mul_f32 v[40:41], v[40:41], v[0:1] op_sel_hi:[1,0]
	global_store_dwordx2 v[46:47], v[34:35], off offset:-512
	v_pk_mul_f32 v[34:35], v[76:77], v[0:1] op_sel_hi:[1,0]
	v_pk_mul_f32 v[36:37], v[78:79], v[0:1] op_sel_hi:[1,0]
	v_pk_mul_f32 v[40:41], v[4:5], v[40:41]
	v_pk_mul_f32 v[38:39], v[2:3], v[38:39]
	v_pk_mul_f32 v[36:37], v[32:33], v[36:37]
	v_pk_mul_f32 v[34:35], v[30:31], v[34:35]
	v_cvt_pk_bf16_f32 v38, v38, v39
	v_cvt_pk_bf16_f32 v39, v40, v41
	v_cvt_pk_bf16_f32 v34, v34, v35
	v_cvt_pk_bf16_f32 v35, v36, v37
	v_cmp_lt_i32_e32 vcc, s22, v42
	global_store_dwordx2 v[46:47], v[38:39], off offset:-3584
	global_store_dwordx2 v[46:47], v[34:35], off
	v_lshl_add_u64 v[46:47], v[46:47], 0, s[14:15]
	s_or_b64 s[16:17], vcc, s[16:17]
	s_andn2_b64 exec, exec, s[16:17]
	s_cbranch_execnz .LBB0_50

; __device__ __forceinline__ unsigned cvt_pk_bf16(float lo, float hi) { f32x2 v = {lo, hi}; bf16x2_t r = __builtin_convertvector(v, bf16x2_t); return __builtin_bit_cast(unsigned, r); }
; __device__ __forceinline__ float wave_sum(float v) {
; #pragma unroll
;     for (int o = 1; o < 64; o <<= 1) v += __shfl_xor(v, o);
;     return v;
; __device__ __forceinline__ void phase_a(KA a, int layer, const float* xin, unsigned char* lds, const int tid_, const int bid_) {
;     ...
;         for (int r8 = 0; r8 < 8; ++r8) {
;             const int m = row0 + r8;
;             const f32x4* xr = (const f32x4*)(xin + (size_t)m * D_) + lane;
;             f32x4 v[8]; float ss = 0.f;
; #pragma unroll
;             for (int j = 0; j < 8; ++j) { v[j] = xr[64 * j]; ss += (v[j].x * v[j].x + v[j].y * v[j].y) + (v[j].z * v[j].z + v[j].w * v[j].w); }
;             ss = wave_sum(ss);
;             const float rstd = rsqrtf(ss * (1.0f / D_) + 1e-6f);
;             u32x2* o8 = (u32x2*)(H + (size_t)m * D_) + lane;
; #pragma unroll
;             for (int j = 0; j < 8; ++j) { v[j] = v[j] * rstd * gn[j]; u32x2 w; w.x = cvt_pk_bf16(v[j].x, v[j].y); w.y = cvt_pk_bf16(v[j].z, v[j].w); o8[64 * j] = w; }
;         }
.LBB0_408:
	v_add_u32_e32 v34, s6, v72
	v_ashrrev_i32_e32 v35, 31, v34
	v_lshlrev_b64 v[36:37], 13, v[34:35]
	v_lshlrev_b64 v[34:35], 12, v[34:35]
	v_lshl_add_u64 v[50:51], v[54:55], 0, v[36:37]
	v_lshl_add_u64 v[88:89], v[56:57], 0, v[34:35]
	global_load_dwordx4 v[34:37], v[50:51], off
	global_load_dwordx4 v[38:41], v[50:51], off offset:1024
	global_load_dwordx4 v[42:45], v[50:51], off offset:2048
	global_load_dwordx4 v[46:49], v[50:51], off offset:3072
	v_add_co_u32_e32 v84, vcc, s23, v50
	s_add_i32 s6, s6, 1
	s_nop 0
	v_addc_co_u32_e32 v85, vcc, 0, v51, vcc
	global_load_dwordx4 v[50:53], v[84:85], off
	global_load_dwordx4 v[64:67], v[84:85], off offset:1024
	global_load_dwordx4 v[80:83], v[84:85], off offset:3072
	s_nop 0
	global_load_dwordx4 v[84:87], v[84:85], off offset:2048
	s_cmp_eq_u32 s6, 8
	s_waitcnt vmcnt(7)
	v_mov_b32_e32 v92, v35
	s_waitcnt vmcnt(6)
	v_mov_b32_e32 v93, v39
	v_mov_b32_e32 v96, v37
	v_mov_b32_e32 v97, v41
	v_mov_b32_e32 v90, v34
	v_mov_b32_e32 v91, v38
	v_mov_b32_e32 v94, v36
	v_mov_b32_e32 v95, v40
	s_waitcnt vmcnt(5)
	v_pk_mul_f32 v[98:99], v[44:45], v[44:45]
	v_pk_mul_f32 v[100:101], v[42:43], v[42:43]
	v_pk_mul_f32 v[92:93], v[92:93], v[92:93]
	v_pk_mul_f32 v[96:97], v[96:97], v[96:97]
	v_pk_mov_b32 v[106:107], v[100:101], v[98:99] op_sel:[1,0]
	v_mov_b32_e32 v101, v99
	v_pk_fma_f32 v[90:91], v[90:91], v[90:91], v[92:93]
	v_pk_fma_f32 v[92:93], v[94:95], v[94:95], v[96:97]
	s_waitcnt vmcnt(4)
	v_mul_f32_e32 v102, v47, v47
	v_mul_f32_e32 v104, v49, v49
	v_pk_add_f32 v[94:95], v[106:107], v[100:101]
	v_pk_add_f32 v[90:91], v[90:91], v[92:93]
	s_waitcnt vmcnt(3)
	v_mul_f32_e32 v59, v50, v50
	v_mul_f32_e32 v79, v51, v51
	v_mul_f32_e32 v111, v52, v52
	v_mul_f32_e32 v113, v53, v53
	v_pk_fma_f32 v[98:99], v[46:47], v[46:47], v[102:103] op_sel_hi:[1,1,0]
	v_pk_fma_f32 v[102:103], v[48:49], v[48:49], v[104:105] op_sel_hi:[1,1,0]
	v_pk_add_f32 v[92:93], v[94:95], v[94:95] op_sel:[0,1] op_sel_hi:[1,0]
	v_pk_add_f32 v[90:91], v[90:91], v[90:91] op_sel:[0,1] op_sel_hi:[1,0]
	s_waitcnt vmcnt(2)
	v_pk_mul_f32 v[104:105], v[66:67], v[66:67]
	v_pk_mul_f32 v[108:109], v[64:65], v[64:65]
	v_mov_b32_e32 v99, v111
	v_mov_b32_e32 v103, v113
	v_mov_b32_e32 v93, v79
	v_mov_b32_e32 v91, v59
	v_pk_mov_b32 v[96:97], v[108:109], v[104:105] op_sel:[1,0]
	v_mov_b32_e32 v109, v105
	v_pk_add_f32 v[94:95], v[98:99], v[102:103]
	v_pk_add_f32 v[90:91], v[90:91], v[92:93]
	s_waitcnt vmcnt(0)
	v_mul_f32_e32 v110, v85, v85
	v_mul_f32_e32 v112, v87, v87
	v_pk_add_f32 v[96:97], v[96:97], v[108:109]
	v_pk_add_f32 v[90:91], v[90:91], v[94:95]
	v_mul_f32_e32 v114, v80, v80
	v_mul_f32_e32 v115, v81, v81
	v_mul_f32_e32 v116, v82, v82
	v_mul_f32_e32 v117, v83, v83
	v_pk_fma_f32 v[100:101], v[84:85], v[84:85], v[110:111] op_sel_hi:[1,1,0]
	v_pk_fma_f32 v[104:105], v[86:87], v[86:87], v[112:113] op_sel_hi:[1,1,0]
	v_pk_add_f32 v[96:97], v[96:97], v[96:97] op_sel:[0,1] op_sel_hi:[1,0]
	v_pk_add_f32 v[90:91], v[90:91], v[90:91] op_sel:[0,1] op_sel_hi:[1,0]
	v_mov_b32_e32 v101, v116
	v_mov_b32_e32 v105, v117
	v_mov_b32_e32 v97, v115
	v_mov_b32_e32 v91, v114
	v_pk_add_f32 v[98:99], v[100:101], v[104:105]
	v_pk_add_f32 v[90:91], v[90:91], v[96:97]
	s_nop 0
	v_pk_add_f32 v[90:91], v[90:91], v[98:99]
	s_nop 0
	v_add_f32_e32 v59, v90, v91
	s_nop 1
	v_add_f32_dpp v59, v59, v59 quad_perm:[1,0,3,2] row_mask:0xf bank_mask:0xf
	s_waitcnt lgkmcnt(0)
	s_nop 1
	v_add_f32_dpp v59, v59, v59 quad_perm:[2,3,0,1] row_mask:0xf bank_mask:0xf
	s_waitcnt lgkmcnt(0)
	s_nop 1
	v_add_f32_dpp v59, v59, v59 row_half_mirror row_mask:0xf bank_mask:0xf
	s_waitcnt lgkmcnt(0)
	s_nop 1
	v_add_f32_dpp v59, v59, v59 row_mirror row_mask:0xf bank_mask:0xf
	s_waitcnt lgkmcnt(0)
	ds_bpermute_b32 v79, v77, v59
	s_waitcnt lgkmcnt(0)
	v_add_f32_e32 v59, v59, v79
	v_mov_b32_e32 v79, v59
	s_nop 1
	v_permlane32_swap_b32_e32 v59, v79
	s_waitcnt lgkmcnt(0)
	v_add_f32_e32 v59, v59, v79
	v_fmamk_f32 v59, v59, 0x3a000000, v227
	v_mul_f32_e32 v79, 0x4b800000, v59
	v_cmp_gt_f32_e32 vcc, s24, v59
	s_nop 1
	v_cndmask_b32_e32 v59, v59, v79, vcc
	v_rsq_f32_e32 v59, v59
	s_nop 0
	v_mul_f32_e32 v79, 0x45800000, v59
	v_cndmask_b32_e32 v90, v59, v79, vcc
	v_pk_mul_f32 v[34:35], v[34:35], v[90:91] op_sel_hi:[1,0]
	v_pk_mul_f32 v[36:37], v[36:37], v[90:91] op_sel_hi:[1,0]
	v_pk_mul_f32 v[38:39], v[38:39], v[90:91] op_sel_hi:[1,0]
	v_pk_mul_f32 v[40:41], v[40:41], v[90:91] op_sel_hi:[1,0]
	v_pk_mul_f32 v[42:43], v[42:43], v[90:91] op_sel_hi:[1,0]
	v_pk_mul_f32 v[44:45], v[44:45], v[90:91] op_sel_hi:[1,0]
	v_pk_mul_f32 v[46:47], v[46:47], v[90:91] op_sel_hi:[1,0]
	v_pk_mul_f32 v[48:49], v[48:49], v[90:91] op_sel_hi:[1,0]
	v_pk_mul_f32 v[50:51], v[50:51], v[90:91] op_sel_hi:[1,0]
	v_pk_mul_f32 v[52:53], v[52:53], v[90:91] op_sel_hi:[1,0]
	v_pk_mul_f32 v[64:65], v[64:65], v[90:91] op_sel_hi:[1,0]
	v_pk_mul_f32 v[66:67], v[66:67], v[90:91] op_sel_hi:[1,0]
	v_pk_mul_f32 v[84:85], v[84:85], v[90:91] op_sel_hi:[1,0]
	v_pk_mul_f32 v[86:87], v[86:87], v[90:91] op_sel_hi:[1,0]
	v_pk_mul_f32 v[80:81], v[80:81], v[90:91] op_sel_hi:[1,0]
	v_pk_mul_f32 v[82:83], v[82:83], v[90:91] op_sel_hi:[1,0]
	v_pk_mul_f32 v[36:37], v[4:5], v[36:37]
	v_pk_mul_f32 v[34:35], v[2:3], v[34:35]
	v_pk_mul_f32 v[40:41], v[8:9], v[40:41]
	v_pk_mul_f32 v[38:39], v[6:7], v[38:39]
	v_pk_mul_f32 v[44:45], v[12:13], v[44:45]
	v_pk_mul_f32 v[42:43], v[10:11], v[42:43]
	v_pk_mul_f32 v[48:49], v[16:17], v[48:49]
	v_pk_mul_f32 v[46:47], v[14:15], v[46:47]
	v_pk_mul_f32 v[52:53], v[20:21], v[52:53]
	v_pk_mul_f32 v[50:51], v[18:19], v[50:51]
	v_pk_mul_f32 v[66:67], v[24:25], v[66:67]
	v_pk_mul_f32 v[64:65], v[22:23], v[64:65]
	v_pk_mul_f32 v[86:87], v[28:29], v[86:87]
	v_pk_mul_f32 v[84:85], v[26:27], v[84:85]
	v_pk_mul_f32 v[82:83], v[32:33], v[82:83]
	v_pk_mul_f32 v[80:81], v[30:31], v[80:81]
	v_cvt_pk_bf16_f32 v34, v34, v35
	v_cvt_pk_bf16_f32 v35, v36, v37
	v_cvt_pk_bf16_f32 v36, v38, v39
	v_cvt_pk_bf16_f32 v37, v40, v41
	v_cvt_pk_bf16_f32 v38, v42, v43
	v_cvt_pk_bf16_f32 v39, v44, v45
	v_cvt_pk_bf16_f32 v40, v46, v47
	v_cvt_pk_bf16_f32 v41, v48, v49
	v_cvt_pk_bf16_f32 v42, v50, v51
	v_cvt_pk_bf16_f32 v43, v52, v53
	v_cvt_pk_bf16_f32 v44, v64, v65
	v_cvt_pk_bf16_f32 v45, v66, v67
	v_cvt_pk_bf16_f32 v46, v84, v85
	v_cvt_pk_bf16_f32 v47, v86, v87
	v_cvt_pk_bf16_f32 v48, v80, v81
	v_cvt_pk_bf16_f32 v49, v82, v83
	global_store_dwordx2 v[88:89], v[34:35], off
	global_store_dwordx2 v[88:89], v[36:37], off offset:512
	global_store_dwordx2 v[88:89], v[38:39], off offset:1024
	global_store_dwordx2 v[88:89], v[40:41], off offset:1536
	global_store_dwordx2 v[88:89], v[42:43], off offset:2048
	global_store_dwordx2 v[88:89], v[44:45], off offset:2560
	global_store_dwordx2 v[88:89], v[46:47], off offset:3072
	global_store_dwordx2 v[88:89], v[48:49], off offset:3584
	s_cbranch_scc0 .LBB0_408
; __device__ __forceinline__ void phase_a(KA a, int layer, const float* xin, unsigned char* lds, const int tid_, const int bid_) {
;     ...
;         asm volatile("s_waitcnt vmcnt(0)" ::: "memory");
;         f32x4 acc = (f32x4){0.f, 0.f, 0.f, 0.f};
;         const bf16_t* arow = H + (size_t)(row0 + (fr & 7)) * D_ + 8 * fq;
	v_ashrrev_i32_e32 v59, 31, v58
	v_lshlrev_b64 v[34:35], 12, v[58:59]
	s_waitcnt vmcnt(0)
	v_lshl_add_u64 v[64:65], v[62:63], 0, v[34:35]
	v_mov_b32_e32 v34, 0
	s_mov_b64 s[6:7], 0
	v_mov_b32_e32 v59, v70
	v_mov_b32_e32 v35, v34
	v_mov_b32_e32 v36, v34
	v_mov_b32_e32 v37, v34

; __device__ __forceinline__ float wave_sum(float v) {
; #pragma unroll
;     for (int o = 1; o < 64; o <<= 1) v += __shfl_xor(v, o);
;     return v;
; __device__ __forceinline__ void phase_final(KA a, const float* x, const int tid_, const int bid_) {
;     ...
;     for (int m = gw; m < T_; m += NGW) {
;         const f32x4* xr = (const f32x4*)(x + (size_t)m * D_) + lane;
;         f32x4 v[8]; float ss = 0.f;
; #pragma unroll
;         for (int j = 0; j < 8; ++j) { v[j] = xr[64 * j]; ss += (v[j].x * v[j].x + v[j].y * v[j].y) + (v[j].z * v[j].z + v[j].w * v[j].w); }
;         ss = wave_sum(ss);
;         const float rstd = rsqrtf(ss * (1.0f / D_) + 1e-6f);
;         f32x4* o = (f32x4*)(a->out + (size_t)m * D_) + lane;
; #pragma unroll
;         for (int j = 0; j < 8; ++j) o[64 * j] = v[j] * rstd * gn[j];
.LBB0_440:
	global_load_dwordx4 v[34:37], v[66:67], off offset:-2048
	global_load_dwordx4 v[38:41], v[66:67], off
	global_load_dwordx4 v[42:45], v[66:67], off offset:-1024
	v_add_co_u32_e32 v68, vcc, 0xfffff000, v66
	v_add_u32_e32 v72, s2, v72
	s_nop 0
	v_addc_co_u32_e32 v69, vcc, -1, v67, vcc
	global_load_dwordx4 v[50:53], v[68:69], off offset:-1024
	global_load_dwordx4 v[46:49], v[66:67], off offset:-4096
	global_load_dwordx4 v[58:61], v[68:69], off offset:-3072
	global_load_dwordx4 v[54:57], v[68:69], off offset:-2048
	global_load_dwordx4 v[62:65], v[66:67], off offset:-3072
	s_waitcnt vmcnt(3)
	v_pk_mul_f32 v[100:101], v[36:37], v[36:37]
	v_pk_mul_f32 v[102:103], v[34:35], v[34:35]
	v_mul_f32_e32 v0, v43, v43
	v_mul_f32_e32 v104, v45, v45
	v_mul_f32_e32 v70, v40, v40
	v_mul_f32_e32 v71, v41, v41
	v_pk_mov_b32 v[106:107], v[102:103], v[100:101] op_sel:[1,0]
	v_mov_b32_e32 v103, v101
	v_pk_fma_f32 v[100:101], v[42:43], v[42:43], v[0:1] op_sel_hi:[1,1,0]
	v_pk_fma_f32 v[104:105], v[44:45], v[44:45], v[104:105] op_sel_hi:[1,1,0]
	v_mov_b32_e32 v101, v70
	v_mov_b32_e32 v105, v71
	v_pk_add_f32 v[80:81], v[106:107], v[102:103]
	v_pk_add_f32 v[70:71], v[100:101], v[104:105]
	v_pk_mul_f32 v[108:109], v[52:53], v[52:53]
	v_pk_mul_f32 v[110:111], v[50:51], v[50:51]
	v_mul_f32_e32 v0, v47, v47
	v_pk_mov_b32 v[82:83], v[110:111], v[108:109] op_sel:[1,0]
	v_mov_b32_e32 v111, v109
	v_pk_add_f32 v[82:83], v[82:83], v[110:111]
	v_pk_add_f32 v[80:81], v[80:81], v[80:81] op_sel:[0,1] op_sel_hi:[1,0]
	v_pk_add_f32 v[82:83], v[82:83], v[82:83] op_sel:[0,1] op_sel_hi:[1,0]
	v_mul_f32_e32 v81, v39, v39
	s_waitcnt vmcnt(2)
	v_mov_b32_e32 v84, v59
	s_waitcnt vmcnt(1)
	v_mov_b32_e32 v85, v55
	v_mov_b32_e32 v108, v58
	v_mov_b32_e32 v109, v54
	v_pk_mul_f32 v[84:85], v[84:85], v[84:85]
	v_mov_b32_e32 v86, v61
	v_mov_b32_e32 v87, v57
	v_pk_fma_f32 v[108:109], v[108:109], v[108:109], v[84:85]
	v_mov_b32_e32 v84, v60
	v_mov_b32_e32 v85, v56
	v_pk_mul_f32 v[86:87], v[86:87], v[86:87]
	s_nop 0
	v_pk_fma_f32 v[84:85], v[84:85], v[84:85], v[86:87]
	v_pk_fma_f32 v[86:87], v[46:47], v[46:47], v[0:1] op_sel_hi:[1,1,0]
	v_pk_add_f32 v[84:85], v[108:109], v[84:85]
	v_mul_f32_e32 v0, v49, v49
	v_pk_fma_f32 v[88:89], v[48:49], v[48:49], v[0:1] op_sel_hi:[1,1,0]
	v_pk_add_f32 v[84:85], v[84:85], v[84:85] op_sel:[0,1] op_sel_hi:[1,0]
	s_waitcnt vmcnt(0)
	v_mul_f32_e32 v87, v64, v64
	v_mul_f32_e32 v89, v65, v65
	v_mul_f32_e32 v83, v63, v63
	v_mul_f32_e32 v85, v62, v62
	v_pk_add_f32 v[86:87], v[86:87], v[88:89]
	v_pk_add_f32 v[82:83], v[84:85], v[82:83]
	s_nop 0
	v_pk_add_f32 v[82:83], v[82:83], v[86:87]
	s_nop 0
	v_pk_add_f32 v[82:83], v[82:83], v[82:83] op_sel:[0,1] op_sel_hi:[1,0]
	s_nop 0
	v_mul_f32_e32 v83, v38, v38
	v_pk_add_f32 v[80:81], v[82:83], v[80:81]
	s_nop 0
	v_pk_add_f32 v[70:71], v[80:81], v[70:71]
	s_nop 0
	v_add_f32_e32 v0, v70, v71
	s_nop 1
	v_add_f32_dpp v0, v0, v0 quad_perm:[1,0,3,2] row_mask:0xf bank_mask:0xf
	s_waitcnt lgkmcnt(0)
	s_nop 1
	v_add_f32_dpp v0, v0, v0 quad_perm:[2,3,0,1] row_mask:0xf bank_mask:0xf
	s_waitcnt lgkmcnt(0)
	s_nop 1
	v_add_f32_dpp v0, v0, v0 row_half_mirror row_mask:0xf bank_mask:0xf
	s_waitcnt lgkmcnt(0)
	s_nop 1
	v_add_f32_dpp v0, v0, v0 row_mirror row_mask:0xf bank_mask:0xf
	s_waitcnt lgkmcnt(0)
	ds_bpermute_b32 v70, v77, v0
	s_waitcnt lgkmcnt(0)
	v_add_f32_e32 v0, v0, v70
	v_mov_b32_e32 v70, v0
	s_nop 1
	v_permlane32_swap_b32_e32 v0, v70
	s_waitcnt lgkmcnt(0)
	v_add_f32_e32 v0, v0, v70
	v_fmamk_f32 v0, v0, 0x3a000000, v227
	v_mul_f32_e32 v70, 0x4b800000, v0
	v_cmp_gt_f32_e32 vcc, s24, v0
	s_nop 1
	v_cndmask_b32_e32 v0, v0, v70, vcc
	v_rsq_f32_e32 v0, v0
	s_nop 0
	v_mul_f32_e32 v70, 0x45800000, v0
	v_cndmask_b32_e32 v0, v0, v70, vcc
	v_pk_mul_f32 v[58:59], v[58:59], v[0:1] op_sel_hi:[1,0]
	v_pk_mul_f32 v[60:61], v[60:61], v[0:1] op_sel_hi:[1,0]
	v_pk_mul_f32 v[54:55], v[54:55], v[0:1] op_sel_hi:[1,0]
	v_pk_mul_f32 v[56:57], v[56:57], v[0:1] op_sel_hi:[1,0]
	v_pk_mul_f32 v[50:51], v[50:51], v[0:1] op_sel_hi:[1,0]
	v_pk_mul_f32 v[52:53], v[52:53], v[0:1] op_sel_hi:[1,0]
	v_pk_mul_f32 v[46:47], v[46:47], v[0:1] op_sel_hi:[1,0]
	v_pk_mul_f32 v[48:49], v[48:49], v[0:1] op_sel_hi:[1,0]
	v_pk_mul_f32 v[62:63], v[62:63], v[0:1] op_sel_hi:[1,0]
	v_pk_mul_f32 v[64:65], v[64:65], v[0:1] op_sel_hi:[1,0]
	v_pk_mul_f32 v[70:71], v[34:35], v[0:1] op_sel_hi:[1,0]
	v_pk_mul_f32 v[80:81], v[36:37], v[0:1] op_sel_hi:[1,0]
	v_pk_mul_f32 v[82:83], v[42:43], v[0:1] op_sel_hi:[1,0]
	v_pk_mul_f32 v[84:85], v[44:45], v[0:1] op_sel_hi:[1,0]
	v_pk_mul_f32 v[86:87], v[38:39], v[0:1] op_sel_hi:[1,0]
	v_pk_mul_f32 v[88:89], v[40:41], v[0:1] op_sel_hi:[1,0]
	v_pk_mul_f32 v[36:37], v[4:5], v[60:61]
	v_pk_mul_f32 v[34:35], v[2:3], v[58:59]
	v_cmp_lt_i32_e32 vcc, s22, v72
	v_pk_mul_f32 v[40:41], v[8:9], v[56:57]
	v_pk_mul_f32 v[38:39], v[6:7], v[54:55]
	v_pk_mul_f32 v[44:45], v[12:13], v[52:53]
	v_pk_mul_f32 v[42:43], v[10:11], v[50:51]
	v_pk_mul_f32 v[48:49], v[16:17], v[48:49]
	v_pk_mul_f32 v[46:47], v[14:15], v[46:47]
	v_pk_mul_f32 v[52:53], v[20:21], v[64:65]
	v_pk_mul_f32 v[50:51], v[18:19], v[62:63]
	v_pk_mul_f32 v[56:57], v[24:25], v[80:81]
	v_pk_mul_f32 v[54:55], v[22:23], v[70:71]
	v_pk_mul_f32 v[60:61], v[28:29], v[84:85]
	v_pk_mul_f32 v[58:59], v[26:27], v[82:83]
	v_pk_mul_f32 v[64:65], v[32:33], v[88:89]
	v_pk_mul_f32 v[62:63], v[30:31], v[86:87]
	s_or_b64 s[8:9], vcc, s[8:9]
	global_store_dwordx4 v[68:69], v[34:37], off offset:-3072
	global_store_dwordx4 v[68:69], v[38:41], off offset:-2048
	global_store_dwordx4 v[68:69], v[42:45], off offset:-1024
	global_store_dwordx4 v[66:67], v[46:49], off offset:-4096
	global_store_dwordx4 v[66:67], v[50:53], off offset:-3072
	global_store_dwordx4 v[66:67], v[54:57], off offset:-2048
	global_store_dwordx4 v[66:67], v[58:61], off offset:-1024
	global_store_dwordx4 v[66:67], v[62:65], off
	v_lshl_add_u64 v[66:67], v[66:67], 0, s[6:7]
	s_andn2_b64 exec, exec, s[8:9]
	s_cbranch_execnz .LBB0_440
